# ssd_pass2: Z-gate tile loads issued in the last block-loop iteration (a whole iteration ahead of the epilogue)
# baseline (speedup 1.0000x reference)
.LBB0_204:
	s_cmp_lt_u32 s22, s18
	s_cselect_b64 s[98:99], -1, 0
	s_cmp_ge_u32 s22, s18
	s_mov_b64 s[0:1], s[24:25]
	s_waitcnt vmcnt(9)
	ds_write_b128 v174, v[0:3] offset:51200
	s_waitcnt vmcnt(8)
	ds_write_b128 v174, v[4:7] offset:59904
	s_waitcnt vmcnt(7)
	ds_write_b128 v133, v[8:11]
	s_waitcnt vmcnt(6)
	ds_write_b128 v133, v[12:15] offset:9216
	s_waitcnt vmcnt(5)
	ds_write_b128 v133, v[16:19] offset:18432
	s_waitcnt vmcnt(4)
	ds_write_b128 v133, v[20:23] offset:27648
	s_waitcnt vmcnt(3)
	ds_write_b128 v133, v[24:27] offset:36864
	s_waitcnt vmcnt(2)
	ds_write_b128 v133, v[28:31] offset:46080
	s_waitcnt vmcnt(1)
	ds_write_b128 v133, v[32:35] offset:55296
	s_waitcnt vmcnt(0)
	ds_write_b128 v133, v[36:39] offset:64512
	s_waitcnt lgkmcnt(0)
	s_barrier
	s_cbranch_scc1 .Lssd_zpf
	v_lshl_add_u64 v[32:33], v[140:141], 0, s[8:9]
	v_add_co_u32_e32 v8, vcc, 0x17600000, v32
	v_add_u32_e32 v2, 32, v138
	s_nop 0
	v_addc_co_u32_e32 v9, vcc, 0, v33, vcc
	v_add_co_u32_e32 v12, vcc, 0x17702000, v32
	v_ashrrev_i32_e32 v139, 31, v138
	s_nop 0
	v_addc_co_u32_e32 v13, vcc, 0, v33, vcc
	v_add_co_u32_e32 v16, vcc, 0x17804000, v32
	v_ashrrev_i32_e32 v3, 31, v2
	s_nop 0
	v_addc_co_u32_e32 v17, vcc, 0, v33, vcc
	v_add_co_u32_e32 v20, vcc, 0x17906000, v32
	v_lshlrev_b64 v[0:1], 10, v[138:139]
	s_nop 0
	v_addc_co_u32_e32 v21, vcc, 0, v33, vcc
	v_add_co_u32_e32 v24, vcc, 0x17a08000, v32
	v_lshlrev_b64 v[2:3], 10, v[2:3]
	s_nop 0
	v_addc_co_u32_e32 v25, vcc, 0, v33, vcc
	v_add_co_u32_e32 v28, vcc, 0x17b0a000, v32
	v_lshl_add_u64 v[0:1], v[134:135], 0, v[0:1]
	s_nop 0
	v_addc_co_u32_e32 v29, vcc, 0, v33, vcc
	v_add_co_u32_e32 v34, vcc, 0x17c0c000, v32
	v_lshl_add_u64 v[4:5], v[134:135], 0, v[2:3]
	s_nop 0
	v_addc_co_u32_e32 v35, vcc, 0, v33, vcc
	v_add_co_u32_e32 v36, vcc, 0x17d0e000, v32
	global_load_dwordx4 v[0:3], v[0:1], off
	s_nop 0
	global_load_dwordx4 v[4:7], v[4:5], off
	v_addc_co_u32_e32 v37, vcc, 0, v33, vcc
	global_load_dwordx4 v[8:11], v[8:9], off offset:128
	s_nop 0
	global_load_dwordx4 v[12:15], v[12:13], off offset:128
	s_nop 0
	global_load_dwordx4 v[16:19], v[16:17], off offset:128
	s_nop 0
	global_load_dwordx4 v[20:23], v[20:21], off offset:128
	s_nop 0
	global_load_dwordx4 v[24:27], v[24:25], off offset:128
	s_nop 0
	global_load_dwordx4 v[28:31], v[28:29], off offset:128
	s_nop 0
	global_load_dwordx4 v[32:35], v[34:35], off offset:128
	s_nop 0
	global_load_dwordx4 v[36:39], v[36:37], off offset:128
	s_or_b64 s[0:1], s[24:25], exec
	s_branch .LBB0_206
.Lssd_zpf:
	v_add_u32_e32 v36, s19, v169
	v_ashrrev_i32_e32 v37, 31, v36
	v_readlane_b32 s2, v251, 24
	v_lshlrev_b64 v[36:37], 12, v[36:37]
	v_readlane_b32 s3, v251, 25
	v_mov_b32_e32 v38, v132
	v_mov_b32_e32 v39, v157
	s_lshl_b32 s28, s17, 1
	v_lshl_add_u64 v[36:37], s[2:3], 0, v[36:37]
	v_lshl_add_u64 v[36:37], v[36:37], 0, s[28:29]
	v_lshl_add_u64 v[36:37], v[36:37], 0, v[38:39]
	global_load_dwordx4 v[28:31], v[36:37], off
	global_load_dwordx4 v[24:27], v[36:37], off offset:128
	global_load_dwordx4 v[20:23], v[36:37], off offset:256
	global_load_dwordx4 v[16:19], v[36:37], off offset:384
	global_load_dwordx4 v[12:15], v[36:37], off offset:512
	global_load_dwordx4 v[8:11], v[36:37], off offset:640
	global_load_dwordx4 v[4:7], v[36:37], off offset:768
	global_load_dwordx4 v[0:3], v[36:37], off offset:896

.LBB0_220:
	s_waitcnt vmcnt(9)
	v_readlane_b32 s0, v251, 24
	v_add_u32_e32 v108, s19, v169
	v_ashrrev_i32_e32 v109, 31, v108
	v_lshlrev_b64 v[108:109], 12, v[108:109]
	v_readlane_b32 s1, v251, 25
	s_ashr_i32 s35, s34, 31
	v_readlane_b32 s40, v254, 20
	s_lshl_b32 s28, s17, 1
	s_lshl_b64 s[0:1], s[34:35], 2
	v_readlane_b32 s50, v254, 30
	v_mov_b32_e32 v133, v157
	v_readlane_b32 s51, v254, 31
	s_add_u32 s0, s50, s0
	s_addc_u32 s1, s51, s1
	v_cmp_lt_i32_e32 vcc, v188, v187
	v_mov_b32_e32 v110, v160
	v_readlane_b32 s0, v253, 62
	s_mov_b32 s56, 0x800000
	v_readlane_b32 s52, v254, 32
	v_add3_u32 v112, s0, v173, v137
	ds_read2_b64 v[104:107], v112 offset1:4
	v_add_u32_e32 v113, 0x1000, v112
	v_add_u32_e32 v118, 0x1800, v112
	s_lshl_b32 s0, s20, 2
	s_add_i32 s0, s0, 16
	s_waitcnt vmcnt(10) lgkmcnt(0)
	v_lshlrev_b32_e32 v32, 16, v104
	v_readlane_b32 s53, v254, 33
	v_readlane_b32 s8, v251, 51
	v_readlane_b32 s9, v251, 52
	v_readlane_b32 s72, v254, 41
	v_readlane_b32 s54, v254, 34
	v_readlane_b32 s55, v254, 35
	v_readlane_b32 s70, v254, 39
	v_readlane_b32 s73, v254, 42
	v_readlane_b32 s74, v254, 44
	v_readlane_b32 s76, v254, 46
	v_readlane_b32 s78, v254, 48
	v_readlane_b32 s82, v254, 52
	v_readlane_b32 s60, v254, 54
	v_readlane_b32 s62, v254, 56
	v_readlane_b32 s64, v254, 58
	v_readlane_b32 s66, v254, 60
	s_movk_i32 s68, 0x2040
	v_readlane_b32 s57, v254, 36
	v_readlane_b32 s58, v254, 37
	v_readlane_b32 s59, v254, 38
	v_readlane_b32 s71, v254, 40
	v_readlane_b32 s69, v254, 43
	v_readlane_b32 s75, v254, 45
	v_readlane_b32 s77, v254, 47
	v_readlane_b32 s79, v254, 49
	v_readlane_b32 s80, v254, 50
	v_readlane_b32 s81, v254, 51
	v_readlane_b32 s83, v254, 53
	v_readlane_b32 s61, v254, 55
	v_readlane_b32 s63, v254, 57
	v_readlane_b32 s65, v254, 59
	v_readlane_b32 s67, v254, 61
	s_movk_i32 s73, 0xf5
	s_movk_i32 s55, 0xfff
	s_mov_b32 s54, 0xf0c0
	v_readlane_b32 s41, v254, 21
	v_readlane_b32 s42, v254, 22
	v_readlane_b32 s43, v254, 23
	v_readlane_b32 s44, v254, 24
	v_readlane_b32 s45, v254, 25
	v_readlane_b32 s46, v254, 26
	v_readlane_b32 s47, v254, 27
	v_readlane_b32 s48, v254, 28
	v_readlane_b32 s49, v254, 29
	v_fma_f32 v111, v110, v32, v40
	v_and_b32_e32 v32, 0xffff0000, v104
	v_fma_f32 v104, v110, v32, v41
	v_lshlrev_b32_e32 v32, 16, v105
	v_fma_f32 v42, v110, v32, v42
	v_and_b32_e32 v32, 0xffff0000, v105
	v_add_u32_e32 v105, 0x800, v112
	ds_read2_b64 v[34:37], v105 offset0:32 offset1:36
	ds_read2_b64 v[38:41], v113 offset0:64 offset1:68
	v_fmac_f32_e32 v43, v110, v32
	ds_read2_b64 v[114:117], v105 offset0:40 offset1:44
	s_waitcnt lgkmcnt(2)
	v_lshlrev_b32_e32 v32, 16, v34
	v_fma_f32 v48, v110, v32, v48
	v_and_b32_e32 v32, 0xffff0000, v34
	v_fma_f32 v49, v110, v32, v49
	v_lshlrev_b32_e32 v32, 16, v35
	v_fma_f32 v50, v110, v32, v50
	v_and_b32_e32 v32, 0xffff0000, v35
	v_fmac_f32_e32 v51, v110, v32
	s_waitcnt lgkmcnt(1)
	v_lshlrev_b32_e32 v32, 16, v38
	v_fma_f32 v44, v110, v32, v44
	v_and_b32_e32 v32, 0xffff0000, v38
	v_fma_f32 v38, v110, v32, v45
	v_lshlrev_b32_e32 v32, 16, v39
	v_fma_f32 v45, v110, v32, v46
	v_and_b32_e32 v32, 0xffff0000, v39
	v_fmac_f32_e32 v47, v110, v32
	ds_read2_b64 v[32:35], v118 offset0:96 offset1:100
	ds_read2_b64 v[118:121], v118 offset0:104 offset1:108
	s_waitcnt lgkmcnt(1)
	v_lshlrev_b32_e32 v46, 16, v33
	v_fma_f32 v46, v110, v46, v54
	v_and_b32_e32 v33, 0xffff0000, v33
	v_and_b32_e32 v54, 0xffff0000, v107
	v_lshlrev_b32_e32 v39, 16, v32
	v_fmac_f32_e32 v55, v110, v33
	v_lshlrev_b32_e32 v33, 16, v106
	v_fmac_f32_e32 v59, v110, v54
	v_lshlrev_b32_e32 v54, 16, v36
	v_and_b32_e32 v36, 0xffff0000, v36
	v_fma_f32 v39, v110, v39, v52
	v_fma_f32 v33, v110, v33, v56
	v_and_b32_e32 v52, 0xffff0000, v106
	v_fma_f32 v56, v110, v36, v61
	v_lshlrev_b32_e32 v36, 16, v37
	v_and_b32_e32 v32, 0xffff0000, v32
	v_fma_f32 v52, v110, v52, v57
	v_fma_f32 v57, v110, v36, v62
	v_and_b32_e32 v36, 0xffff0000, v37
	v_fma_f32 v32, v110, v32, v53
	v_lshlrev_b32_e32 v53, 16, v107
	v_fmac_f32_e32 v63, v110, v36
	v_lshlrev_b32_e32 v36, 16, v40
	v_fma_f32 v53, v110, v53, v58
	v_fma_f32 v58, v110, v36, v64
	v_and_b32_e32 v36, 0xffff0000, v40
	v_fma_f32 v40, v110, v36, v65
	v_lshlrev_b32_e32 v36, 16, v41
	v_fma_f32 v54, v110, v54, v60
	v_fma_f32 v60, v110, v36, v66
	v_and_b32_e32 v36, 0xffff0000, v41
	v_fmac_f32_e32 v67, v110, v36
	v_lshlrev_b32_e32 v36, 16, v34
	v_and_b32_e32 v34, 0xffff0000, v34
	v_fma_f32 v61, v110, v34, v81
	v_lshlrev_b32_e32 v34, 16, v35
	v_fma_f32 v62, v110, v34, v82
	v_and_b32_e32 v34, 0xffff0000, v35
	v_fma_f32 v41, v110, v36, v80
	v_fmac_f32_e32 v83, v110, v34
	ds_read2_b64 v[34:37], v112 offset0:8 offset1:12
	v_and_b32_e32 v66, 0xffff0000, v114
	v_fma_f32 v66, v110, v66, v73
	v_and_b32_e32 v73, 0xffff0000, v115
	v_and_b32_e32 v80, 0xffff0000, v116
	s_waitcnt lgkmcnt(0)
	v_lshlrev_b32_e32 v65, 16, v35
	v_fma_f32 v65, v110, v65, v78
	v_lshlrev_b32_e32 v78, 16, v37
	v_fma_f32 v78, v110, v78, v90
	v_and_b32_e32 v37, 0xffff0000, v37
	v_and_b32_e32 v90, 0xffff0000, v121
	v_and_b32_e32 v35, 0xffff0000, v35
	v_fmac_f32_e32 v91, v110, v37
	v_lshlrev_b32_e32 v37, 16, v116
	v_fmac_f32_e32 v103, v110, v90
	v_lshl_add_u32 v90, v171, 2, s0
	s_movk_i32 s0, 0x2040
	v_fmac_f32_e32 v79, v110, v35
	v_lshlrev_b32_e32 v35, 16, v114
	v_fma_f32 v37, v110, v37, v92
	v_mad_u32_u24 v92, v172, s0, v90
	v_fma_f32 v35, v110, v35, v72
	v_lshlrev_b32_e32 v72, 16, v115
	ds_read2_b64 v[112:115], v113 offset0:72 offset1:76
	s_waitcnt lgkmcnt(0)
	s_barrier
	ds_write2_b32 v92, v111, v48 offset1:16
	v_add_u32_e32 v48, 0x800, v92
	ds_write2_b32 v48, v104, v49 offset0:4 offset1:20
	v_add_u32_e32 v49, 0x1000, v92
	ds_write2_b32 v49, v42, v50 offset0:8 offset1:24
	v_add_u32_e32 v42, 0x1800, v92
	ds_write2_b32 v42, v43, v51 offset0:12 offset1:28
	ds_write2_b32 v92, v44, v39 offset0:32 offset1:48
	ds_write2_b32 v48, v38, v32 offset0:36 offset1:52
	ds_write2_b32 v49, v45, v46 offset0:40 offset1:56
	ds_write2_b32 v42, v47, v55 offset0:44 offset1:60
	v_add_u32_e32 v32, 0x8000, v92
	ds_write2_b32 v32, v33, v54 offset0:64 offset1:80
	v_add_u32_e32 v33, 0x8800, v92
	v_add_u32_e32 v38, 0x9000, v92
	v_add_u32_e32 v39, 0x9800, v92
	ds_write2_b32 v33, v52, v56 offset0:68 offset1:84
	ds_write2_b32 v38, v53, v57 offset0:72 offset1:88
	ds_write2_b32 v39, v59, v63 offset0:76 offset1:92
	ds_write2_b32 v32, v58, v41 offset0:96 offset1:112
	ds_write2_b32 v33, v40, v61 offset0:100 offset1:116
	ds_write2_b32 v38, v60, v62 offset0:104 offset1:120
	ds_write2_b32 v39, v67, v83 offset0:108 offset1:124
	v_mov_b32_e32 v32, 0x10200
	v_lshlrev_b32_e32 v64, 16, v34
	v_mad_u32_u24 v32, v172, s0, v32
	v_fma_f32 v64, v110, v64, v76
	v_add_u32_e32 v33, v90, v32
	ds_write_b32 v33, v64
	v_mov_b32_e32 v33, 0x10a10
	v_and_b32_e32 v34, 0xffff0000, v34
	v_mad_u32_u24 v33, v172, s0, v33
	v_fma_f32 v34, v110, v34, v77
	v_add_u32_e32 v38, v90, v33
	ds_write_b32 v38, v34
	v_mov_b32_e32 v34, 0x11220
	v_mad_u32_u24 v34, v172, s0, v34
	v_add_u32_e32 v38, v90, v34
	ds_write_b32 v38, v65
	v_mov_b32_e32 v38, 0x11a30
	v_mad_u32_u24 v38, v172, s0, v38
	v_fmac_f32_e32 v75, v110, v73
	v_lshlrev_b32_e32 v73, 16, v112
	v_fma_f32 v80, v110, v80, v93
	v_add_u32_e32 v93, 64, v90
	v_add_u32_e32 v39, v90, v38
	v_fma_f32 v68, v110, v73, v68
	v_and_b32_e32 v73, 0xffff0000, v112
	ds_write_b32 v39, v79
	v_add_u32_e32 v39, v93, v32
	v_fma_f32 v69, v110, v73, v69
	v_lshlrev_b32_e32 v73, 16, v113
	ds_write_b32 v39, v35
	v_add_u32_e32 v35, v93, v33
	v_fma_f32 v72, v110, v72, v74
	v_fma_f32 v70, v110, v73, v70
	v_and_b32_e32 v73, 0xffff0000, v113
	ds_write_b32 v35, v66
	v_add_u32_e32 v35, v93, v34
	v_fmac_f32_e32 v71, v110, v73
	v_lshlrev_b32_e32 v73, 16, v118
	v_add_u32_e32 v43, 0x80, v90
	v_add_u32_e32 v50, 0xc0, v90
	ds_write_b32 v35, v72
	v_add_u32_e32 v35, v93, v38
	v_fma_f32 v73, v110, v73, v84
	v_and_b32_e32 v74, 0xffff0000, v118
	ds_write_b32 v35, v75
	v_add_u32_e32 v35, v43, v32
	v_add_u32_e32 v32, v50, v32
	v_fma_f32 v74, v110, v74, v85
	v_lshlrev_b32_e32 v76, 16, v119
	ds_write_b32 v32, v73
	v_add_u32_e32 v32, v50, v33
	v_fma_f32 v76, v110, v76, v86
	v_and_b32_e32 v77, 0xffff0000, v119
	ds_write_b32 v32, v74
	v_add_u32_e32 v32, v50, v34
	v_fmac_f32_e32 v87, v110, v77
	ds_write_b32 v32, v76
	v_add_u32_e32 v32, v50, v38
	ds_write_b32 v32, v87
	v_mov_b32_e32 v32, 0x18300
	v_lshlrev_b32_e32 v77, 16, v36
	v_mad_u32_u24 v32, v172, s0, v32
	v_fma_f32 v77, v110, v77, v88
	ds_write_b32 v35, v68
	v_add_u32_e32 v35, v43, v33
	v_add_u32_e32 v33, v90, v32
	ds_write_b32 v33, v77
	v_mov_b32_e32 v33, 0x18b10
	v_and_b32_e32 v36, 0xffff0000, v36
	v_mad_u32_u24 v33, v172, s0, v33
	v_fma_f32 v36, v110, v36, v89
	ds_write_b32 v35, v69
	v_add_u32_e32 v35, v43, v34
	v_add_u32_e32 v34, v90, v33
	ds_write_b32 v34, v36
	v_mov_b32_e32 v34, 0x19320
	ds_write_b32 v35, v70
	v_add_u32_e32 v35, v43, v38
	v_mad_u32_u24 v34, v172, s0, v34
	ds_write_b32 v35, v71
	v_add_u32_e32 v35, v90, v34
	ds_write_b32 v35, v78
	v_mad_u32_u24 v35, v172, s0, v198
	v_add_u32_e32 v36, v90, v35
	ds_write_b32 v36, v91
	v_add_u32_e32 v36, v93, v32
	v_lshlrev_b32_e32 v81, 16, v117
	ds_write_b32 v36, v37
	v_add_u32_e32 v36, v93, v33
	v_fma_f32 v81, v110, v81, v94
	v_and_b32_e32 v82, 0xffff0000, v117
	v_and_b32_e32 v86, 0xffff0000, v115
	ds_write_b32 v36, v80
	v_add_u32_e32 v36, v93, v34
	v_fmac_f32_e32 v95, v110, v82
	v_fmac_f32_e32 v99, v110, v86
	v_lshlrev_b32_e32 v86, 16, v120
	ds_write_b32 v36, v81
	v_add_u32_e32 v36, v93, v35
	v_fma_f32 v86, v110, v86, v100
	v_and_b32_e32 v88, 0xffff0000, v120
	ds_write_b32 v36, v95
	v_add_u32_e32 v36, v43, v32
	v_add_u32_e32 v32, v50, v32
	v_lshlrev_b32_e32 v82, 16, v114
	v_fma_f32 v88, v110, v88, v101
	v_lshlrev_b32_e32 v89, 16, v121
	ds_write_b32 v32, v86
	v_add_u32_e32 v32, v50, v33
	v_fma_f32 v82, v110, v82, v96
	v_and_b32_e32 v84, 0xffff0000, v114
	v_fma_f32 v89, v110, v89, v102
	ds_write_b32 v32, v88
	v_add_u32_e32 v32, v50, v34
	v_fma_f32 v84, v110, v84, v97
	v_lshlrev_b32_e32 v85, 16, v115
	ds_write_b32 v36, v82
	v_add_u32_e32 v36, v43, v33
	ds_write_b32 v32, v89
	v_add_u32_e32 v32, v50, v35
	s_movk_i32 s0, 0x810
	v_fma_f32 v85, v110, v85, v98
	ds_write_b32 v36, v84
	v_add_u32_e32 v36, v43, v34
	ds_write_b32 v32, v103
	v_mul_lo_u32 v33, v169, s0
	v_lshlrev_b32_e32 v32, 2, v166
	ds_write_b32 v36, v85
	v_add_u32_e32 v36, v43, v35
	v_add3_u32 v76, 16, v33, v32
	ds_write_b32 v36, v99
	s_waitcnt lgkmcnt(0)
	s_barrier
	ds_read_b128 v[34:37], v76
	ds_read_b128 v[38:41], v76 offset:16
	s_waitcnt vmcnt(0)
	s_lshl_b32 s2, s17, 2
	s_add_u32 s2, s52, s2
	s_addc_u32 s3, s53, 0
	global_load_dwordx4 v[204:207], v32, s[2:3] offset:16
	global_load_dwordx4 v[208:211], v32, s[2:3]
	global_load_dwordx4 v[212:215], v32, s[2:3] offset:272
	global_load_dwordx4 v[216:219], v32, s[2:3] offset:256
	global_load_dwordx4 v[220:223], v32, s[2:3] offset:528
	global_load_dwordx4 v[224:227], v32, s[2:3] offset:512
	global_load_dwordx4 v[228:231], v32, s[2:3] offset:784
	global_load_dwordx4 v[232:235], v32, s[2:3] offset:768
	global_load_dwordx4 v[236:239], v32, s[2:3] offset:1040
	global_load_dwordx4 v[240:243], v32, s[2:3] offset:1024
	global_load_dwordx4 v[146:149], v32, s[2:3] offset:1296
	global_load_dwordx4 v[150:153], v32, s[2:3] offset:1280
	global_load_dwordx4 v[168:171], v32, s[2:3] offset:1552
	global_load_dwordx4 v[172:175], v32, s[2:3] offset:1536
	global_load_dwordx4 v[176:179], v32, s[2:3] offset:1808
	v_lshlrev_b32_e32 v33, 16, v28
	v_and_b32_e32 v28, 0xffff0000, v28
	v_lshlrev_b32_e32 v42, 16, v29
	s_waitcnt lgkmcnt(1)
	v_mul_f32_e32 v72, v35, v28
	v_mul_f32_e32 v73, v34, v33
	v_mul_f32_e32 v77, v72, v72
	v_and_b32_e32 v29, 0xffff0000, v29
	v_mul_f32_e32 v71, v36, v42
	v_fmac_f32_e32 v77, v73, v73
	v_lshlrev_b32_e32 v43, 16, v30
	v_and_b32_e32 v30, 0xffff0000, v30
	v_lshlrev_b32_e32 v44, 16, v31
	v_and_b32_e32 v31, 0xffff0000, v31
	v_mul_f32_e32 v70, v37, v29
	v_fmac_f32_e32 v77, v71, v71
	s_waitcnt lgkmcnt(0)
	v_mul_f32_e32 v69, v38, v43
	v_mul_f32_e32 v68, v39, v30
	v_mul_f32_e32 v65, v41, v31
	v_fmac_f32_e32 v77, v70, v70
	ds_read_b128 v[28:31], v76 offset:256
	ds_read_b128 v[34:37], v76 offset:272
	v_fmac_f32_e32 v77, v69, v69
	v_mul_f32_e32 v67, v40, v44
	v_fmac_f32_e32 v77, v68, v68
	v_fmac_f32_e32 v77, v67, v67
	v_lshlrev_b32_e32 v33, 16, v24
	v_fmac_f32_e32 v77, v65, v65
	v_and_b32_e32 v24, 0xffff0000, v24
	s_waitcnt lgkmcnt(1)
	v_mul_f32_e32 v66, v28, v33
	v_lshlrev_b32_e32 v38, 16, v25
	v_mul_f32_e32 v63, v29, v24
	v_fmac_f32_e32 v77, v66, v66
	v_and_b32_e32 v25, 0xffff0000, v25
	v_mul_f32_e32 v60, v30, v38
	v_fmac_f32_e32 v77, v63, v63
	v_lshlrev_b32_e32 v39, 16, v26
	v_and_b32_e32 v26, 0xffff0000, v26
	v_lshlrev_b32_e32 v40, 16, v27
	v_and_b32_e32 v27, 0xffff0000, v27
	v_mul_f32_e32 v56, v31, v25
	v_fmac_f32_e32 v77, v60, v60
	s_waitcnt lgkmcnt(0)
	v_mul_f32_e32 v51, v34, v39
	v_mul_f32_e32 v45, v35, v26
	v_mul_f32_e32 v35, v37, v27
	v_fmac_f32_e32 v77, v56, v56
	ds_read_b128 v[24:27], v76 offset:512
	ds_read_b128 v[28:31], v76 offset:528
	v_fmac_f32_e32 v77, v51, v51
	v_mul_f32_e32 v40, v36, v40
	v_fmac_f32_e32 v77, v45, v45
	v_fmac_f32_e32 v77, v40, v40
	v_lshlrev_b32_e32 v33, 16, v20
	v_fmac_f32_e32 v77, v35, v35
	v_and_b32_e32 v20, 0xffff0000, v20
	s_waitcnt lgkmcnt(1)
	v_mul_f32_e32 v64, v24, v33
	v_lshlrev_b32_e32 v34, 16, v21
	v_mul_f32_e32 v61, v25, v20
	v_fmac_f32_e32 v77, v64, v64
	v_and_b32_e32 v21, 0xffff0000, v21
	v_mul_f32_e32 v57, v26, v34
	v_fmac_f32_e32 v77, v61, v61
	v_lshlrev_b32_e32 v36, 16, v22
	v_and_b32_e32 v22, 0xffff0000, v22
	v_lshlrev_b32_e32 v37, 16, v23
	v_and_b32_e32 v23, 0xffff0000, v23
	v_mul_f32_e32 v52, v27, v21
	v_fmac_f32_e32 v77, v57, v57
	s_waitcnt lgkmcnt(0)
	v_mul_f32_e32 v46, v28, v36
	v_mul_f32_e32 v41, v29, v22
	v_mul_f32_e32 v36, v30, v37
	v_mul_f32_e32 v30, v31, v23
	v_fmac_f32_e32 v77, v52, v52
	ds_read_b128 v[20:23], v76 offset:768
	ds_read_b128 v[24:27], v76 offset:784
	v_fmac_f32_e32 v77, v46, v46
	v_fmac_f32_e32 v77, v41, v41
	v_fmac_f32_e32 v77, v36, v36
	v_lshlrev_b32_e32 v28, 16, v16
	v_fmac_f32_e32 v77, v30, v30
	v_and_b32_e32 v16, 0xffff0000, v16
	s_waitcnt lgkmcnt(1)
	v_mul_f32_e32 v62, v20, v28
	v_lshlrev_b32_e32 v29, 16, v17
	v_mul_f32_e32 v58, v21, v16
	v_fmac_f32_e32 v77, v62, v62
	v_and_b32_e32 v17, 0xffff0000, v17
	v_mul_f32_e32 v53, v22, v29
	v_fmac_f32_e32 v77, v58, v58
	v_lshlrev_b32_e32 v31, 16, v18
	v_and_b32_e32 v18, 0xffff0000, v18
	v_lshlrev_b32_e32 v33, 16, v19
	v_and_b32_e32 v19, 0xffff0000, v19
	v_mul_f32_e32 v47, v23, v17
	v_fmac_f32_e32 v77, v53, v53
	s_waitcnt lgkmcnt(0)
	v_mul_f32_e32 v42, v24, v31
	v_mul_f32_e32 v37, v25, v18
	v_mul_f32_e32 v27, v27, v19
	v_fmac_f32_e32 v77, v47, v47
	ds_read_b128 v[16:19], v76 offset:1024
	ds_read_b128 v[20:23], v76 offset:1040
	v_fmac_f32_e32 v77, v42, v42
	v_mul_f32_e32 v31, v26, v33
	v_fmac_f32_e32 v77, v37, v37
	v_fmac_f32_e32 v77, v31, v31
	v_lshlrev_b32_e32 v24, 16, v12
	v_fmac_f32_e32 v77, v27, v27
	v_and_b32_e32 v12, 0xffff0000, v12
	s_waitcnt lgkmcnt(1)
	v_mul_f32_e32 v59, v16, v24
	v_lshlrev_b32_e32 v25, 16, v13
	v_mul_f32_e32 v54, v17, v12
	v_fmac_f32_e32 v77, v59, v59
	v_and_b32_e32 v13, 0xffff0000, v13
	v_mul_f32_e32 v48, v18, v25
	v_fmac_f32_e32 v77, v54, v54
	v_lshlrev_b32_e32 v26, 16, v14
	v_and_b32_e32 v14, 0xffff0000, v14
	v_lshlrev_b32_e32 v28, 16, v15
	v_and_b32_e32 v15, 0xffff0000, v15
	v_mul_f32_e32 v43, v19, v13
	v_fmac_f32_e32 v77, v48, v48
	s_waitcnt lgkmcnt(0)
	v_mul_f32_e32 v38, v20, v26
	v_mul_f32_e32 v33, v21, v14
	v_mul_f32_e32 v24, v23, v15
	v_fmac_f32_e32 v77, v43, v43
	ds_read_b128 v[12:15], v76 offset:1280
	ds_read_b128 v[16:19], v76 offset:1296
	v_fmac_f32_e32 v77, v38, v38
	v_mul_f32_e32 v28, v22, v28
	v_fmac_f32_e32 v77, v33, v33
	v_fmac_f32_e32 v77, v28, v28
	v_lshlrev_b32_e32 v20, 16, v8
	v_fmac_f32_e32 v77, v24, v24
	v_and_b32_e32 v8, 0xffff0000, v8
	s_waitcnt lgkmcnt(1)
	v_mul_f32_e32 v55, v12, v20
	v_lshlrev_b32_e32 v21, 16, v9
	v_mul_f32_e32 v49, v13, v8
	v_fmac_f32_e32 v77, v55, v55
	v_and_b32_e32 v9, 0xffff0000, v9
	v_mul_f32_e32 v44, v14, v21
	v_fmac_f32_e32 v77, v49, v49
	v_lshlrev_b32_e32 v22, 16, v10
	v_and_b32_e32 v10, 0xffff0000, v10
	v_lshlrev_b32_e32 v23, 16, v11
	v_and_b32_e32 v11, 0xffff0000, v11
	v_mul_f32_e32 v39, v15, v9
	v_fmac_f32_e32 v77, v44, v44
	s_waitcnt lgkmcnt(0)
	v_mul_f32_e32 v34, v16, v22
	v_mul_f32_e32 v29, v17, v10
	v_mul_f32_e32 v25, v18, v23
	v_mul_f32_e32 v23, v19, v11
	v_fmac_f32_e32 v77, v39, v39
	ds_read_b128 v[8:11], v76 offset:1536
	ds_read_b128 v[12:15], v76 offset:1552
	v_fmac_f32_e32 v77, v34, v34
	v_fmac_f32_e32 v77, v29, v29
	v_fmac_f32_e32 v77, v25, v25
	v_lshlrev_b32_e32 v16, 16, v4
	v_fmac_f32_e32 v77, v23, v23
	v_and_b32_e32 v4, 0xffff0000, v4
	s_waitcnt lgkmcnt(1)
	v_mul_f32_e32 v50, v8, v16
	v_lshlrev_b32_e32 v17, 16, v5
	v_and_b32_e32 v5, 0xffff0000, v5
	v_lshlrev_b32_e32 v18, 16, v6
	v_and_b32_e32 v6, 0xffff0000, v6
	v_lshlrev_b32_e32 v74, 16, v7
	v_and_b32_e32 v7, 0xffff0000, v7
	v_mul_f32_e32 v26, v9, v4
	v_fmac_f32_e32 v77, v50, v50
	v_mul_f32_e32 v22, v10, v17
	v_mul_f32_e32 v21, v11, v5
	s_waitcnt lgkmcnt(0)
	v_mul_f32_e32 v20, v12, v18
	v_mul_f32_e32 v19, v13, v6
	v_mul_f32_e32 v18, v14, v74
	v_mul_f32_e32 v17, v15, v7
	v_fmac_f32_e32 v77, v26, v26
	v_lshlrev_b32_e32 v4, 16, v0
	v_and_b32_e32 v5, 0xffff0000, v0
	v_lshlrev_b32_e32 v6, 16, v1
	v_and_b32_e32 v7, 0xffff0000, v1
	v_lshlrev_b32_e32 v8, 16, v2
	v_and_b32_e32 v9, 0xffff0000, v2
	v_lshlrev_b32_e32 v74, 16, v3
	v_and_b32_e32 v75, 0xffff0000, v3
	ds_read_b128 v[0:3], v76 offset:1792
	v_fmac_f32_e32 v77, v22, v22
	v_fmac_f32_e32 v77, v21, v21
	v_fmac_f32_e32 v77, v20, v20
	v_fmac_f32_e32 v77, v19, v19
	v_fmac_f32_e32 v77, v18, v18
	s_waitcnt lgkmcnt(0)
	v_pk_mul_f32 v[14:15], v[0:1], v[4:5]
	v_fmac_f32_e32 v77, v17, v17
	v_pk_mul_f32 v[0:1], v[14:15], v[14:15]
	v_pk_mul_f32 v[12:13], v[2:3], v[6:7]
	v_add_f32_e32 v0, v77, v0
	v_add_f32_e32 v4, v0, v1
	v_pk_mul_f32 v[0:1], v[12:13], v[12:13]
	s_lshl_b32 s0, s17, 2
	v_add_f32_e32 v0, v4, v0
	v_add_f32_e32 v4, v0, v1
	ds_read_b128 v[0:3], v76 offset:1808
	s_add_u32 s0, s52, s0
	s_addc_u32 s1, s53, 0
	s_waitcnt lgkmcnt(0)
	v_pk_mul_f32 v[10:11], v[0:1], v[8:9]
	s_nop 0
	v_pk_mul_f32 v[0:1], v[10:11], v[10:11]
	v_pk_mul_f32 v[8:9], v[2:3], v[74:75]
	v_add_f32_e32 v0, v4, v0
	v_add_f32_e32 v4, v0, v1
	v_pk_mul_f32 v[0:1], v[8:9], v[8:9]
	s_nop 0
	v_add_f32_e32 v0, v4, v0
	v_add_f32_e32 v0, v0, v1
	v_cndmask_b32_e32 v1, v185, v188, vcc
	v_lshlrev_b32_e32 v1, 2, v1
	ds_bpermute_b32 v1, v1, v0
	v_cmp_lt_i32_e32 vcc, v189, v187
	s_waitcnt lgkmcnt(0)
	v_add_f32_e32 v0, v0, v1
	v_cndmask_b32_e32 v1, v185, v189, vcc
	v_lshlrev_b32_e32 v1, 2, v1
	ds_bpermute_b32 v1, v1, v0
	v_cmp_lt_i32_e32 vcc, v190, v187
	s_waitcnt lgkmcnt(0)
	v_add_f32_e32 v0, v0, v1
	v_cndmask_b32_e32 v1, v185, v190, vcc
	v_lshlrev_b32_e32 v1, 2, v1
	ds_bpermute_b32 v1, v1, v0
	s_waitcnt lgkmcnt(0)
	v_add_f32_e32 v0, v0, v1
	v_fmamk_f32 v0, v0, 0x3b000000, v182
	v_cmp_gt_f32_e32 vcc, s56, v0
	v_mul_f32_e32 v1, 0x4b800000, v0
	s_nop 0
	v_cndmask_b32_e32 v0, v0, v1, vcc
	v_rsq_f32_e32 v0, v0
	s_nop 0
	v_mul_f32_e32 v1, 0x45800000, v0
	v_cndmask_b32_e32 v16, v0, v1, vcc
	global_load_dwordx4 v[142:145], v32, s[0:1] offset:1792
	v_mul_f32_e32 v73, v73, v16
	v_mul_f32_e32 v69, v69, v16
	v_mul_f32_e32 v68, v68, v16
	v_mul_f32_e32 v67, v67, v16
	v_mul_f32_e32 v72, v72, v16
	v_mul_f32_e32 v71, v71, v16
	v_mul_f32_e32 v70, v70, v16
	v_mul_f32_e32 v51, v51, v16
	v_mul_f32_e32 v60, v60, v16
	v_mul_f32_e32 v56, v56, v16
	v_mul_f32_e32 v20, v20, v16
	v_mul_f32_e32 v22, v22, v16
	v_mul_f32_e32 v21, v21, v16
	v_mul_f32_e32 v10, v10, v16
	v_mul_f32_e32 v12, v12, v16
	v_mul_f32_e32 v13, v13, v16
	s_waitcnt vmcnt(15)
	v_mul_f32_e32 v0, v204, v69
	s_waitcnt vmcnt(14)
	v_mul_f32_e32 v4, v208, v73
	v_mul_f32_e32 v1, v205, v68
	v_mul_f32_e32 v67, v206, v67
	v_mul_f32_e32 v2, v65, v16
	v_mul_f32_e32 v5, v209, v72
	v_mul_f32_e32 v65, v207, v2
	v_cvt_pk_bf16_f32 v2, v4, v5
	v_cvt_pk_bf16_f32 v4, v0, v1
	v_lshl_add_u64 v[0:1], s[8:9], 0, v[108:109]
	v_lshl_add_u64 v[0:1], v[0:1], 0, s[28:29]
	v_lshl_add_u64 v[0:1], v[0:1], 0, v[132:133]
	v_mul_f32_e32 v6, v210, v71
	v_mul_f32_e32 v7, v211, v70
	v_cvt_pk_bf16_f32 v3, v6, v7
	v_cvt_pk_bf16_f32 v5, v67, v65
	global_store_dwordx4 v[0:1], v[2:5], off
	v_mul_f32_e32 v6, v66, v16
	v_mul_f32_e32 v7, v63, v16
	s_waitcnt vmcnt(14)
	v_mul_f32_e32 v51, v51, v212
	v_mul_f32_e32 v2, v45, v16
	v_mul_f32_e32 v45, v2, v213
	v_mul_f32_e32 v2, v40, v16
	v_mul_f32_e32 v40, v2, v214
	v_mul_f32_e32 v2, v35, v16
	v_mul_f32_e32 v5, v2, v215
	s_waitcnt vmcnt(13)
	v_mul_f32_e32 v6, v6, v216
	v_mul_f32_e32 v7, v7, v217
	v_mul_f32_e32 v60, v60, v218
	v_mul_f32_e32 v56, v56, v219
	v_cvt_pk_bf16_f32 v2, v6, v7
	v_cvt_pk_bf16_f32 v3, v60, v56
	v_cvt_pk_bf16_f32 v4, v51, v45
	v_cvt_pk_bf16_f32 v5, v40, v5
	global_store_dwordx4 v[0:1], v[2:5], off offset:128
	v_mul_f32_e32 v45, v46, v16
	v_mul_f32_e32 v6, v64, v16
	v_mul_f32_e32 v7, v61, v16
	v_mul_f32_e32 v35, v57, v16
	v_mul_f32_e32 v40, v52, v16
	s_waitcnt vmcnt(13)
	v_mul_f32_e32 v45, v45, v220
	v_mul_f32_e32 v2, v41, v16
	v_mul_f32_e32 v41, v2, v221
	v_mul_f32_e32 v2, v36, v16
	v_mul_f32_e32 v36, v2, v222
	v_mul_f32_e32 v2, v30, v16
	v_mul_f32_e32 v5, v2, v223
	s_waitcnt vmcnt(12)
	v_mul_f32_e32 v6, v6, v224
	v_mul_f32_e32 v7, v7, v225
	v_mul_f32_e32 v35, v35, v226
	v_mul_f32_e32 v40, v40, v227
	v_cvt_pk_bf16_f32 v2, v6, v7
	v_cvt_pk_bf16_f32 v3, v35, v40
	v_cvt_pk_bf16_f32 v4, v45, v41
	v_cvt_pk_bf16_f32 v5, v36, v5
	global_store_dwordx4 v[0:1], v[2:5], off offset:256
	v_mul_f32_e32 v36, v42, v16
	v_mul_f32_e32 v6, v62, v16
	v_mul_f32_e32 v7, v58, v16
	v_mul_f32_e32 v30, v53, v16
	v_mul_f32_e32 v35, v47, v16
	s_waitcnt vmcnt(12)
	v_mul_f32_e32 v36, v36, v228
	v_mul_f32_e32 v2, v37, v16
	v_mul_f32_e32 v37, v2, v229
	v_mul_f32_e32 v2, v31, v16
	v_mul_f32_e32 v31, v2, v230
	v_mul_f32_e32 v2, v27, v16
	v_mul_f32_e32 v5, v2, v231
	s_waitcnt vmcnt(11)
	v_mul_f32_e32 v6, v6, v232
	v_mul_f32_e32 v7, v7, v233
	v_mul_f32_e32 v30, v30, v234
	v_mul_f32_e32 v35, v35, v235
	v_cvt_pk_bf16_f32 v2, v6, v7
	v_cvt_pk_bf16_f32 v3, v30, v35
	v_cvt_pk_bf16_f32 v4, v36, v37
	v_cvt_pk_bf16_f32 v5, v31, v5
	global_store_dwordx4 v[0:1], v[2:5], off offset:384
	v_mul_f32_e32 v31, v38, v16
	v_mul_f32_e32 v6, v59, v16
	v_mul_f32_e32 v7, v54, v16
	v_mul_f32_e32 v27, v48, v16
	v_mul_f32_e32 v30, v43, v16
	s_waitcnt vmcnt(11)
	v_mul_f32_e32 v31, v31, v236
	v_mul_f32_e32 v2, v33, v16
	v_mul_f32_e32 v33, v2, v237
	v_mul_f32_e32 v2, v28, v16
	v_mul_f32_e32 v28, v2, v238
	v_mul_f32_e32 v2, v24, v16
	v_mul_f32_e32 v5, v2, v239
	s_waitcnt vmcnt(10)
	v_mul_f32_e32 v6, v6, v240
	v_mul_f32_e32 v7, v7, v241
	v_mul_f32_e32 v27, v27, v242
	v_mul_f32_e32 v30, v30, v243
	v_cvt_pk_bf16_f32 v2, v6, v7
	v_cvt_pk_bf16_f32 v3, v27, v30
	v_cvt_pk_bf16_f32 v4, v31, v33
	v_cvt_pk_bf16_f32 v5, v28, v5
	global_store_dwordx4 v[0:1], v[2:5], off offset:512
	v_mul_f32_e32 v28, v34, v16
	v_mul_f32_e32 v6, v55, v16
	v_mul_f32_e32 v7, v49, v16
	v_mul_f32_e32 v24, v44, v16
	v_mul_f32_e32 v27, v39, v16
	s_waitcnt vmcnt(10)
	v_mul_f32_e32 v28, v28, v146
	v_mul_f32_e32 v2, v29, v16
	v_mul_f32_e32 v29, v2, v147
	v_mul_f32_e32 v2, v25, v16
	v_mul_f32_e32 v25, v2, v148
	v_mul_f32_e32 v2, v23, v16
	v_mul_f32_e32 v5, v2, v149
	s_waitcnt vmcnt(9)
	v_mul_f32_e32 v6, v6, v150
	v_mul_f32_e32 v7, v7, v151
	v_mul_f32_e32 v24, v24, v152
	v_mul_f32_e32 v27, v27, v153
	v_cvt_pk_bf16_f32 v2, v6, v7
	v_cvt_pk_bf16_f32 v3, v24, v27
	v_cvt_pk_bf16_f32 v4, v28, v29
	v_cvt_pk_bf16_f32 v5, v25, v5
	global_store_dwordx4 v[0:1], v[2:5], off offset:640
	v_mul_f32_e32 v6, v50, v16
	v_mul_f32_e32 v7, v26, v16
	s_waitcnt vmcnt(9)
	v_mul_f32_e32 v20, v20, v168
	v_mul_f32_e32 v2, v19, v16
	v_mul_f32_e32 v19, v2, v169
	v_mul_f32_e32 v2, v18, v16
	v_mul_f32_e32 v18, v2, v170
	v_mul_f32_e32 v2, v17, v16
	v_mul_f32_e32 v5, v2, v171
	s_waitcnt vmcnt(8)
	v_mul_f32_e32 v6, v6, v172
	v_mul_f32_e32 v7, v7, v173
	v_mul_f32_e32 v22, v22, v174
	v_mul_f32_e32 v21, v21, v175
	v_cvt_pk_bf16_f32 v2, v6, v7
	v_cvt_pk_bf16_f32 v3, v22, v21
	v_cvt_pk_bf16_f32 v4, v20, v19
	v_cvt_pk_bf16_f32 v5, v18, v5
	global_store_dwordx4 v[0:1], v[2:5], off offset:768
	v_mul_f32_e32 v6, v14, v16
	v_mul_f32_e32 v7, v15, v16
	s_mov_b64 s[0:1], 0
	s_waitcnt vmcnt(8)
	v_mul_f32_e32 v10, v10, v176
	v_mul_f32_e32 v2, v11, v16
	v_mul_f32_e32 v11, v2, v177
	v_mul_f32_e32 v2, v8, v16
	v_mul_f32_e32 v8, v2, v178
	v_mul_f32_e32 v2, v9, v16
	v_mul_f32_e32 v5, v2, v179
	s_waitcnt vmcnt(7)
	v_mul_f32_e32 v6, v6, v142
	v_mul_f32_e32 v7, v7, v143
	v_mul_f32_e32 v12, v12, v144
	v_mul_f32_e32 v13, v13, v145
	v_cvt_pk_bf16_f32 v2, v6, v7
	v_cvt_pk_bf16_f32 v3, v12, v13
	v_cvt_pk_bf16_f32 v4, v10, v11
	v_cvt_pk_bf16_f32 v5, v8, v5
	global_store_dwordx4 v[0:1], v[2:5], off offset:896
	s_barrier
